# GEMM static wave priority level 3 instead of 1 for waves 0-3
# speedup vs baseline: 1.0020x; 1.0020x over previous
; #define PG8_STAGE(bufoff, gbase, voff) do { _Pragma("unroll") for (int _i = 0; _i < 2; ++_i) \
;         __builtin_amdgcn_global_load_lds((const unsigned*)((const char*)(gbase) + (voff)[_i]), (PG8_LAS unsigned*)(lds + (bufoff) + ldsw + _i * 8192), 16, 0, 0); } while (0)
; #define PG8_WAIT_V(n) asm volatile("s_waitcnt vmcnt(" #n ")" ::: "memory")
; #define PG8_BAR __builtin_amdgcn_s_barrier()
; template <class Epi, class Sched, bool STAMP = false>
; __device__ __forceinline__ void gemm_phase(PG8_LAS unsigned char* lds, const Gemm g, const Sched& S, const Epi& E, unsigned long long* stamps) {
;     ...
;     for (int i = 0; i < 2; ++i) { int R, C; stage_rc(tid * 16 + i * 8192, R, C); const int Rb = Epi::PERM ? ((R & ~31) + perm32(R & 31)) : R;
;         voffA[i] = (unsigned)(R * K + C) * 2u; voffB[i] = (unsigned)(Rb * K + C) * 2u; }
;     const size_t kstep = (size_t)(BK * 2);
;     const size_t hstep = (size_t)HALF * K * 2;
;     const size_t tstep = 2 * hstep;
;     const unsigned ldsw = (unsigned)wid * 1024u;
;     const int aoff = lds_byte(wr * 64 + fr, fq * 8), boff = lds_byte(wc * 32 + fr, fq * 8);
;     ...
;     Unit cur, nxt; int ui = 0;
;     if (!S.next(0, cur)) return;
;     f32x4 acc[2][2][4][2];
; #pragma unroll
;     for (int a = 0; a < 2; ++a)
; #pragma unroll
;         for (int b = 0; b < 2; ++b)
; #pragma unroll
;             for (int m = 0; m < 4; ++m)
; #pragma unroll
;                 for (int n = 0; n < 2; ++n) acc[a][b][m][n] = (f32x4){0.f, 0.f, 0.f, 0.f};
;     bf16x8 At[4][2], B0[2][2], B1[2][2];
;     const char* cA = (const char*)g.A + (size_t)cur.pm * tstep; const char* cB = (const char*)g.Bt + (size_t)cur.pn * tstep;
;     S.a_ready(cur);
;     PG8_STAGE(PG8_SB(0, 0), cB, voffB); PG8_STAGE(PG8_SA(0, 0), cA, voffA); PG8_STAGE(PG8_SB(0, 1), cB + hstep, voffB); PG8_STAGE(PG8_SA(0, 1), cA + hstep, voffA);
;     if (wr == 1) PG8_BAR;
;     PG8_WAIT_V(4); PG8_BAR;
;     PG8_STAGE(PG8_SB(1, 0), cB + kstep, voffB); PG8_STAGE(PG8_SA(1, 0), cA + kstep, voffA); PG8_STAGE(PG8_SB(1, 1), cB + hstep + kstep, voffB);
;     PG8_WAIT_V(6); PG8_BAR;
.LBB0_736:
	v_mov_b32_e32 v165, v0
	v_lshrrev_b32_e32 v22, 1, v9
	v_lshl_add_u64 v[10:11], s[88:89], 0, v[164:165]
	v_mov_b32_e32 v171, v0
	v_and_b32_e32 v216, 24, v22
	v_lshl_add_u64 v[12:13], s[88:89], 0, v[170:171]
	v_mov_b32_e32 v163, v0
	v_and_b32_e32 v1, 15, v9
	v_lshlrev_b32_e32 v22, 1, v216
	v_lshlrev_b32_e32 v9, 2, v9
	s_add_i32 m0, s80, 0x18000
	v_lshl_add_u64 v[10:11], v[10:11], 0, s[10:11]
	v_lshl_add_u64 v[14:15], s[22:23], 0, v[162:163]
	v_mov_b32_e32 v167, v0
	v_lshl_add_u64 v[18:19], s[0:1], 0, v[164:165]
	v_lshl_add_u64 v[20:21], s[0:1], 0, v[170:171]
	v_lshl_or_b32 v22, v1, 6, v22
	s_lshl_b32 s0, s30, 13
	v_and_b32_e32 v9, 32, v9
	s_waitcnt vmcnt(4)
	s_barrier
	global_load_lds_dwordx4 v[10:11], off
	v_lshl_add_u64 v[10:11], v[12:13], 0, s[10:11]
	s_add_i32 m0, s80, 0x1a000
	s_add_i32 s33, s80, 0x8000
	v_lshl_add_u64 v[16:17], s[22:23], 0, v[166:167]
	v_bitop3_b32 v23, v22, s0, v9 bitop3:0xde
	s_lshl_b32 s0, s28, 5
	global_load_lds_dwordx4 v[10:11], off
	v_lshl_add_u64 v[10:11], v[14:15], 0, s[10:11]
	s_mov_b32 m0, s33
	s_add_i32 s28, s80, 0xa000
	global_load_lds_dwordx4 v[10:11], off
	v_lshl_add_u64 v[10:11], v[16:17], 0, s[10:11]
	s_mov_b32 m0, s28
	v_rcp_iflag_f32_e32 v2, v2
	global_load_lds_dwordx4 v[10:11], off
	s_add_i32 m0, s80, 0x1c000
	v_lshl_add_u64 v[10:11], v[18:19], 0, s[10:11]
	global_load_lds_dwordx4 v[10:11], off
	v_lshl_add_u64 v[10:11], v[20:21], 0, s[10:11]
	s_add_i32 m0, s80, 0x1e000
	v_mul_f32_e32 v2, 0x4f7ffffe, v2
	global_load_lds_dwordx4 v[10:11], off
	v_cvt_u32_f32_e32 v2, v2
	s_and_b32 s72, s0, 0x60
	s_lshl_b32 s0, s72, 7
	v_bitop3_b32 v217, v22, s0, v9 bitop3:0xde
	v_readfirstlane_b32 s1, v2
	v_add_u32_e32 v2, v5, v3
	s_sub_i32 s0, 0, s73
	v_add_lshl_u32 v2, v2, v4, 1
	v_mov_b32_e32 v3, v0
	s_waitcnt vmcnt(6)
	s_mul_i32 s0, s0, s1
	v_lshl_add_u64 v[172:173], s[94:95], 0, v[2:3]
	v_add_u32_e32 v2, v8, v6
	s_lshr_b32 s26, s4, 6
	s_mul_hi_u32 s0, s1, s0
	v_add_lshl_u32 v2, v2, v7, 1
	s_lshl_b32 s5, s30, 6
	s_add_i32 s4, s26, -2
	s_mov_b32 s69, s95
	s_lshr_b32 s34, s68, 3
	s_mov_b32 s70, 0
	s_add_i32 s71, s1, s0
	v_lshl_add_u64 v[174:175], s[94:95], 0, v[2:3]
	v_add_u32_e32 v218, 0, v23
	v_readfirstlane_b32 s98, v169
	s_cmpk_lt_u32 s98, 0x100
	s_cbranch_scc0 .Lg_prio_skip
	s_setprio 3
